# stacked: barrier waiters poll arrival counter (TOP), SB epilogue gate prefetch + write-through Y stores, on top of convert-loop overlap
# speedup vs baseline: 1.0379x; 1.0045x over previous
.LBB0_335:
	global_atomic_add v4, v[170:171], v212, off sc0
	v_cvt_f32_u32_e32 v2, v3
	v_sub_u32_e32 v5, 0, v3
	v_rcp_iflag_f32_e32 v2, v2
	s_nop 0
	v_mul_f32_e32 v2, 0x4f7ffffe, v2
	v_cvt_u32_f32_e32 v2, v2
	v_mul_lo_u32 v5, v5, v2
	v_mul_hi_u32 v5, v2, v5
	v_add_u32_e32 v2, v2, v5
	s_waitcnt vmcnt(0)
	v_mul_hi_u32 v2, v4, v2
	v_mul_lo_u32 v5, v2, v3
	v_sub_u32_e32 v5, v4, v5
	v_add_u32_e32 v6, 1, v2
	v_sub_u32_e32 v7, v5, v3
	v_cmp_ge_u32_e32 vcc, v5, v3
	v_add_u32_e32 v4, 1, v4
	s_nop 0
	v_cndmask_b32_e32 v2, v2, v6, vcc
	v_cndmask_b32_e32 v5, v5, v7, vcc
	v_add_u32_e32 v6, 1, v2
	v_cmp_ge_u32_e32 vcc, v5, v3
	s_nop 1
	v_cndmask_b32_e32 v2, v2, v6, vcc
	v_mul_lo_u32 v5, v3, v2
	v_add_u32_e32 v3, v5, v3
	v_cmp_ne_u32_e32 vcc, v4, v3
	s_and_saveexec_b64 s[4:5], vcc
	s_xor_b64 s[6:7], exec, s[4:5]
	s_cbranch_execz .LBB0_349
	s_waitcnt lgkmcnt(0)
	v_mad_u32_u24 v6, v2, v1, v1
	v_mov_b32_e32 v1, 0x3200
	global_load_dword v1, v1, s[22:23] sc1
	s_waitcnt vmcnt(0)
	v_cmp_gt_u32_e32 vcc, v6, v1
	s_and_saveexec_b64 s[8:9], vcc
	s_cbranch_execz .LBB0_348
	s_mov_b32 s3, 1
	s_mov_b64 s[24:25], 0
	s_branch .LBB0_339

.LBB0_341:
	v_mov_b32_e32 v1, 0x3200
	global_load_dword v1, v1, s[22:23] sc1
	s_add_i32 s3, s3, 1
	s_mov_b64 s[40:41], -1
	s_waitcnt vmcnt(0)
	v_cmp_le_u32_e32 vcc, v6, v1
	s_orn2_b64 s[38:39], vcc, exec
	s_branch .LBB0_338

.LBB0_352:
	s_or_b64 exec, exec, s[24:25]
	v_cvt_f32_u32_e32 v4, v1
	s_waitcnt vmcnt(0)
	v_readfirstlane_b32 s3, v3
	v_sub_u32_e32 v3, 0, v1
	v_readlane_b32 s4, v248, 41
	v_rcp_iflag_f32_e32 v4, v4
	v_add_u32_e32 v2, s3, v2
	v_add_u32_e32 v5, 1, v2
	v_readlane_b32 s5, v248, 42
	v_mul_f32_e32 v4, 0x4f7ffffe, v4
	v_cvt_u32_f32_e32 v4, v4
	s_mov_b64 s[24:25], -1
	v_mul_lo_u32 v3, v3, v4
	v_mul_hi_u32 v3, v4, v3
	v_add_u32_e32 v3, v4, v3
	v_mul_hi_u32 v3, v2, v3
	v_mul_lo_u32 v4, v3, v1
	v_sub_u32_e32 v2, v2, v4
	v_add_u32_e32 v6, 1, v3
	v_sub_u32_e32 v4, v2, v1
	v_cmp_ge_u32_e32 vcc, v2, v1
	s_nop 1
	v_cndmask_b32_e32 v3, v3, v6, vcc
	v_cndmask_b32_e32 v2, v2, v4, vcc
	v_add_u32_e32 v4, 1, v3
	v_cmp_ge_u32_e32 vcc, v2, v1
	s_nop 1
	v_cndmask_b32_e32 v4, v3, v4, vcc
	v_mul_lo_u32 v2, v1, v4
	v_add_u32_e32 v1, v2, v1
	v_cmp_ne_u32_e32 vcc, v5, v1
	v_mov_b32_e32 v7, v1
	v_mov_b64_e32 v[2:3], s[4:5]
	s_and_saveexec_b64 s[8:9], vcc
	s_cbranch_execz .LBB0_364
	v_readlane_b32 s4, v248, 41
	v_readlane_b32 s5, v248, 42
	s_mov_b64 s[36:37], 0
	s_nop 3
	global_load_dword v1, v0, s[4:5] offset:-256 sc1
	s_waitcnt vmcnt(0)
	v_cmp_gt_u32_e32 vcc, v7, v1
	s_and_saveexec_b64 s[24:25], vcc
	s_cbranch_execz .LBB0_363
	s_mov_b32 s3, 1
	s_branch .LBB0_356

.LBB0_358:
	v_readlane_b32 s4, v248, 41
	v_readlane_b32 s5, v248, 42
	s_add_i32 s3, s3, 1
	s_mov_b64 s[44:45], -1
	s_nop 2
	global_load_dword v1, v0, s[4:5] offset:-256 sc1
	s_waitcnt vmcnt(0)
	v_cmp_le_u32_e32 vcc, v7, v1
	s_orn2_b64 s[40:41], vcc, exec
	s_branch .LBB0_355

.LBB0_472:
	global_atomic_add v4, v[170:171], v212, off sc0
	v_cvt_f32_u32_e32 v1, v3
	v_sub_u32_e32 v5, 0, v3
	v_rcp_iflag_f32_e32 v1, v1
	s_nop 0
	v_mul_f32_e32 v1, 0x4f7ffffe, v1
	v_cvt_u32_f32_e32 v1, v1
	v_mul_lo_u32 v5, v5, v1
	v_mul_hi_u32 v5, v1, v5
	v_add_u32_e32 v1, v1, v5
	s_waitcnt vmcnt(0)
	v_mul_hi_u32 v1, v4, v1
	v_mul_lo_u32 v5, v1, v3
	v_sub_u32_e32 v5, v4, v5
	v_add_u32_e32 v6, 1, v1
	v_cmp_ge_u32_e32 vcc, v5, v3
	v_add_u32_e32 v4, 1, v4
	s_nop 0
	v_cndmask_b32_e32 v1, v1, v6, vcc
	v_sub_u32_e32 v6, v5, v3
	v_cndmask_b32_e32 v5, v5, v6, vcc
	v_add_u32_e32 v6, 1, v1
	v_cmp_ge_u32_e32 vcc, v5, v3
	s_nop 1
	v_cndmask_b32_e32 v1, v1, v6, vcc
	v_mul_lo_u32 v5, v3, v1
	v_add_u32_e32 v3, v5, v3
	v_cmp_ne_u32_e32 vcc, v4, v3
	s_and_saveexec_b64 s[4:5], vcc
	s_xor_b64 s[6:7], exec, s[4:5]
	s_cbranch_execz .LBB0_486
	s_waitcnt lgkmcnt(0)
	v_mad_u32_u24 v6, v1, v2, v2
	v_mov_b32_e32 v2, 0x3200
	global_load_dword v2, v2, s[22:23] sc1
	s_waitcnt vmcnt(0)
	v_cmp_gt_u32_e32 vcc, v6, v2
	s_and_saveexec_b64 s[8:9], vcc
	s_cbranch_execz .LBB0_485
	s_mov_b32 s3, 1
	s_mov_b64 s[36:37], 0
	s_branch .LBB0_476

.LBB0_478:
	v_mov_b32_e32 v2, 0x3200
	global_load_dword v2, v2, s[22:23] sc1
	s_add_i32 s3, s3, 1
	s_mov_b64 s[44:45], -1
	s_waitcnt vmcnt(0)
	v_cmp_le_u32_e32 vcc, v6, v2
	s_orn2_b64 s[40:41], vcc, exec
	s_branch .LBB0_475

.LBB0_489:
	s_or_b64 exec, exec, s[36:37]
	s_waitcnt vmcnt(0)
	v_readfirstlane_b32 s3, v3
	v_sub_u32_e32 v4, 0, v2
	v_readlane_b32 s4, v248, 41
	v_add_u32_e32 v3, s3, v1
	v_cvt_f32_u32_e32 v1, v2
	v_readlane_b32 s5, v248, 42
	s_mov_b64 s[36:37], -1
	v_rcp_iflag_f32_e32 v1, v1
	s_nop 0
	v_mul_f32_e32 v1, 0x4f7ffffe, v1
	v_cvt_u32_f32_e32 v1, v1
	v_mul_lo_u32 v4, v4, v1
	v_mul_hi_u32 v4, v1, v4
	v_add_u32_e32 v1, v1, v4
	v_mul_hi_u32 v1, v3, v1
	v_mul_lo_u32 v4, v1, v2
	v_sub_u32_e32 v4, v3, v4
	v_cmp_ge_u32_e32 vcc, v4, v2
	v_add_u32_e32 v5, 1, v1
	v_add_u32_e32 v3, 1, v3
	v_cndmask_b32_e32 v1, v1, v5, vcc
	v_sub_u32_e32 v5, v4, v2
	v_cndmask_b32_e32 v4, v4, v5, vcc
	v_cmp_ge_u32_e32 vcc, v4, v2
	v_add_u32_e32 v4, 1, v1
	s_nop 0
	v_cndmask_b32_e32 v1, v1, v4, vcc
	v_mul_lo_u32 v4, v2, v1
	v_add_u32_e32 v2, v4, v2
	v_cmp_ne_u32_e32 vcc, v3, v2
	v_mov_b32_e32 v7, v2
	v_mov_b64_e32 v[2:3], s[4:5]
	s_and_saveexec_b64 s[8:9], vcc
	s_cbranch_execz .LBB0_501
	v_readlane_b32 s4, v248, 41
	v_readlane_b32 s5, v248, 42
	s_mov_b64 s[38:39], 0
	s_nop 3
	global_load_dword v2, v0, s[4:5] offset:-256 sc1
	s_waitcnt vmcnt(0)
	v_cmp_gt_u32_e32 vcc, v7, v2
	s_and_saveexec_b64 s[36:37], vcc
	s_cbranch_execz .LBB0_500
	s_mov_b32 s3, 1
	s_branch .LBB0_493

.LBB0_495:
	v_readlane_b32 s4, v248, 41
	v_readlane_b32 s5, v248, 42
	s_add_i32 s3, s3, 1
	s_mov_b64 s[46:47], -1
	s_nop 2
	global_load_dword v2, v0, s[4:5] offset:-256 sc1
	s_waitcnt vmcnt(0)
	v_cmp_le_u32_e32 vcc, v7, v2
	s_orn2_b64 s[44:45], vcc, exec
	s_branch .LBB0_492

.LBB0_736:
	global_atomic_add v4, v[170:171], v212, off sc0
	v_cvt_f32_u32_e32 v1, v3
	v_sub_u32_e32 v5, 0, v3
	v_rcp_iflag_f32_e32 v1, v1
	s_nop 0
	v_mul_f32_e32 v1, 0x4f7ffffe, v1
	v_cvt_u32_f32_e32 v1, v1
	v_mul_lo_u32 v5, v5, v1
	v_mul_hi_u32 v5, v1, v5
	v_add_u32_e32 v1, v1, v5
	s_waitcnt vmcnt(0)
	v_mul_hi_u32 v1, v4, v1
	v_mul_lo_u32 v5, v1, v3
	v_sub_u32_e32 v5, v4, v5
	v_add_u32_e32 v6, 1, v1
	v_cmp_ge_u32_e32 vcc, v5, v3
	v_add_u32_e32 v4, 1, v4
	s_nop 0
	v_cndmask_b32_e32 v1, v1, v6, vcc
	v_sub_u32_e32 v6, v5, v3
	v_cndmask_b32_e32 v5, v5, v6, vcc
	v_add_u32_e32 v6, 1, v1
	v_cmp_ge_u32_e32 vcc, v5, v3
	s_nop 1
	v_cndmask_b32_e32 v1, v1, v6, vcc
	v_mul_lo_u32 v5, v3, v1
	v_add_u32_e32 v3, v5, v3
	v_cmp_ne_u32_e32 vcc, v4, v3
	s_and_saveexec_b64 s[4:5], vcc
	s_xor_b64 s[6:7], exec, s[4:5]
	s_cbranch_execz .LBB0_750
	s_waitcnt lgkmcnt(0)
	v_mad_u32_u24 v6, v1, v2, v2
	v_mov_b32_e32 v2, 0x3200
	global_load_dword v2, v2, s[22:23] sc1
	s_waitcnt vmcnt(0)
	v_cmp_gt_u32_e32 vcc, v6, v2
	s_and_saveexec_b64 s[8:9], vcc
	s_cbranch_execz .LBB0_749
	s_mov_b32 s3, 1
	s_mov_b64 s[24:25], 0
	s_branch .LBB0_740

.LBB0_742:
	v_mov_b32_e32 v2, 0x3200
	global_load_dword v2, v2, s[22:23] sc1
	s_add_i32 s3, s3, 1
	s_mov_b64 s[40:41], -1
	s_waitcnt vmcnt(0)
	v_cmp_le_u32_e32 vcc, v6, v2
	s_orn2_b64 s[38:39], vcc, exec
	s_branch .LBB0_739

.LBB0_753:
	s_or_b64 exec, exec, s[8:9]
	s_waitcnt vmcnt(0)
	v_readfirstlane_b32 s3, v3
	v_sub_u32_e32 v4, 0, v2
	v_readlane_b32 s4, v248, 41
	v_add_u32_e32 v3, s3, v1
	v_cvt_f32_u32_e32 v1, v2
	v_readlane_b32 s5, v248, 42
	s_mov_b64 s[8:9], -1
	v_rcp_iflag_f32_e32 v1, v1
	s_nop 0
	v_mul_f32_e32 v1, 0x4f7ffffe, v1
	v_cvt_u32_f32_e32 v1, v1
	v_mul_lo_u32 v4, v4, v1
	v_mul_hi_u32 v4, v1, v4
	v_add_u32_e32 v1, v1, v4
	v_mul_hi_u32 v1, v3, v1
	v_mul_lo_u32 v4, v1, v2
	v_sub_u32_e32 v4, v3, v4
	v_cmp_ge_u32_e32 vcc, v4, v2
	v_add_u32_e32 v5, 1, v1
	v_add_u32_e32 v3, 1, v3
	v_cndmask_b32_e32 v1, v1, v5, vcc
	v_sub_u32_e32 v5, v4, v2
	v_cndmask_b32_e32 v4, v4, v5, vcc
	v_cmp_ge_u32_e32 vcc, v4, v2
	v_add_u32_e32 v4, 1, v1
	s_nop 0
	v_cndmask_b32_e32 v1, v1, v4, vcc
	v_mul_lo_u32 v4, v2, v1
	v_add_u32_e32 v2, v4, v2
	v_cmp_ne_u32_e32 vcc, v3, v2
	v_mov_b32_e32 v7, v2
	v_mov_b64_e32 v[2:3], s[4:5]
	s_and_saveexec_b64 s[6:7], vcc
	s_cbranch_execz .LBB0_765
	v_readlane_b32 s4, v248, 41
	v_readlane_b32 s5, v248, 42
	s_mov_b64 s[24:25], 0
	s_nop 3
	global_load_dword v2, v0, s[4:5] offset:-256 sc1
	s_waitcnt vmcnt(0)
	v_cmp_gt_u32_e32 vcc, v7, v2
	s_and_saveexec_b64 s[8:9], vcc
	s_cbranch_execz .LBB0_764
	s_mov_b32 s3, 1
	s_branch .LBB0_757

.LBB0_759:
	v_readlane_b32 s4, v248, 41
	v_readlane_b32 s5, v248, 42
	s_add_i32 s3, s3, 1
	s_mov_b64 s[40:41], -1
	s_nop 2
	global_load_dword v2, v0, s[4:5] offset:-256 sc1
	s_waitcnt vmcnt(0)
	v_cmp_le_u32_e32 vcc, v7, v2
	s_orn2_b64 s[38:39], vcc, exec
	s_branch .LBB0_756
